# v026 + P6 (out-projection + f32 residual) epilogue written by hand: rolling-window residual loads added straight from scratch registers, DPP lane-pair exchange, stepped store addresses, the eight row
# speedup vs baseline: 1.0044x; 1.0027x over previous
; __device__ __forceinline__ unsigned cvt_pk_bf16(float lo, float hi) { const cvt_f32x2_t v = {lo, hi}; const cvt_bf16x2_t b = __builtin_convertvector(v, cvt_bf16x2_t); return __builtin_bit_cast(unsigned, b); }
;     __device__ __forceinline__ void operator()(const f32x4 (&acc)[2][2][4][2], const Unit& u, int wr, int wc, int fr, int fq) const {
;         const int col0 = u.pn * BM + wc * 64 + 8 * fq;
; #pragma unroll
;         for (int ai = 0; ai < 2; ++ai)
; #pragma unroll
;             for (int m = 0; m < 4; ++m) { const int rowg = u.pm * BM + ai * HALF + wr * 64 + m * 16, row = rowg + fr; const size_t off = (size_t)row * 1024 + col0;
;                 u32x4 w[2]; float ss = 0.f;
; #pragma unroll
;                 for (int bj = 0; bj < 2; ++bj) { f32x4 b0, b1;
;                     if (BASE_F32) { const float* bp = (const float*)base + off + 32 * bj; b0 = *(const f32x4*)bp; b1 = *(const f32x4*)(bp + 4); }
;                     else { const u32x4 bb = *(const u32x4*)((const bf16_t*)base + off + 32 * bj);
;                         b0 = (f32x4){__uint_as_float(bb.x << 16), __uint_as_float(bb.x & 0xffff0000u), __uint_as_float(bb.y << 16), __uint_as_float(bb.y & 0xffff0000u)};
;                         b1 = (f32x4){__uint_as_float(bb.z << 16), __uint_as_float(bb.z & 0xffff0000u), __uint_as_float(bb.w << 16), __uint_as_float(bb.w & 0xffff0000u)}; }
;                     const f32x4 o0 = b0 + acc[ai][bj][m][0], o1 = b1 + acc[ai][bj][m][1];
;                     ss += ((o0[0] * o0[0] + o0[1] * o0[1]) + (o0[2] * o0[2] + o0[3] * o0[3])) + ((o1[0] * o1[0] + o1[1] * o1[1]) + (o1[2] * o1[2] + o1[3] * o1[3]));
;                     w[bj].x = cvt_pk_bf16(o0[0], o0[1]); w[bj].y = cvt_pk_bf16(o0[2], o0[3]); w[bj].z = cvt_pk_bf16(o1[0], o1[1]); w[bj].w = cvt_pk_bf16(o1[2], o1[3]); }
;                 ss += __shfl_xor(ss, 16); ss += __shfl_xor(ss, 32); if (fq == 0) slots[(size_t)row * 16 + u.pn * 4 + wc] = ss;
;                 wide_store(xb, 1024, rowg, col0, fr, w[0], w[1]);
.LBB0_588:
	s_lshl_b32 s19, s48, 8
	s_add_i32 s19, s19, s56
	v_or_b32_e32 v148, s19, v150
	v_ashrrev_i32_e32 v149, 31, v148
	v_readlane_b32 s64, v239, 10
	v_readlane_b32 s65, v239, 11
	v_readlane_b32 s30, v239, 49
	v_readlane_b32 s31, v239, 50
	v_lshl_or_b32 v146, s10, 8, v156
	v_ashrrev_i32_e32 v147, 31, v146
	v_lshlrev_b64 v[234:235], 12, v[148:149]
	s_mov_b32 s99, 0
	v_lshl_add_u64 v[234:235], s[64:65], 0, v[234:235]
	v_lshl_add_u64 v[234:235], v[146:147], 2, v[234:235]
	global_load_dwordx4 v[180:183], v[234:235], off
	global_load_dwordx4 v[184:187], v[234:235], off offset:16
	global_load_dwordx4 v[188:191], v[234:235], off offset:128
	global_load_dwordx4 v[192:195], v[234:235], off offset:144
	s_mov_b32 s98, 0x10000
	v_lshl_add_u64 v[168:169], v[234:235], 0, s[98:99]
	global_load_dwordx4 v[196:199], v[168:169], off
	global_load_dwordx4 v[200:203], v[168:169], off offset:16
	global_load_dwordx4 v[204:207], v[168:169], off offset:128
	global_load_dwordx4 v[208:211], v[168:169], off offset:144
	s_mov_b32 s98, 0x20000
	v_lshl_add_u64 v[168:169], v[234:235], 0, s[98:99]
	global_load_dwordx4 v[212:215], v[168:169], off
	global_load_dwordx4 v[216:219], v[168:169], off offset:16
	global_load_dwordx4 v[220:223], v[168:169], off offset:128
	global_load_dwordx4 v[224:227], v[168:169], off offset:144
	s_mov_b32 s98, 0x30000
	v_lshl_add_u64 v[168:169], v[234:235], 0, s[98:99]
	global_load_dwordx4 v[240:243], v[168:169], off
	global_load_dwordx4 v[244:247], v[168:169], off offset:16
	global_load_dwordx4 v[248:251], v[168:169], off offset:128
	global_load_dwordx4 v[252:255], v[168:169], off offset:144
	v_lshlrev_b64 v[236:237], 6, v[148:149]
	v_lshl_add_u64 v[236:237], s[82:83], 0, v[236:237]
	s_lshl_b32 s0, s10, 4
	s_lshl_b32 s1, s55, 2
	s_add_i32 s0, s0, s1
	s_mov_b32 s1, 0
	v_lshl_add_u64 v[236:237], v[236:237], 0, s[0:1]
	v_or_b32_e32 v162, s19, v151
	v_ashrrev_i32_e32 v163, 31, v162
	v_lshlrev_b64 v[162:163], 11, v[162:163]
	v_lshl_add_u64 v[162:163], s[30:31], 0, v[162:163]
	v_lshl_add_u64 v[162:163], v[146:147], 1, v[162:163]
	v_lshl_add_u64 v[164:165], v[162:163], 0, v[136:137]
	v_xor_b32_e32 v161, 16, v160
	v_xor_b32_e32 v178, 32, v160
	v_lshlrev_b32_e32 v161, 2, v161
	v_lshlrev_b32_e32 v178, 2, v178
	s_waitcnt vmcnt(12)
	v_pk_add_f32 v[124:125], v[124:125], v[180:181]
	v_pk_add_f32 v[126:127], v[126:127], v[182:183]
	v_pk_add_f32 v[120:121], v[120:121], v[184:185]
	v_pk_add_f32 v[122:123], v[122:123], v[186:187]
	v_pk_add_f32 v[116:117], v[116:117], v[188:189]
	v_pk_add_f32 v[118:119], v[118:119], v[190:191]
	v_pk_add_f32 v[112:113], v[112:113], v[192:193]
	v_pk_add_f32 v[114:115], v[114:115], v[194:195]
	s_mov_b32 s98, 0x80000
	v_lshl_add_u64 v[168:169], v[234:235], 0, s[98:99]
	global_load_dwordx4 v[180:183], v[168:169], off
	global_load_dwordx4 v[184:187], v[168:169], off offset:16
	global_load_dwordx4 v[188:191], v[168:169], off offset:128
	global_load_dwordx4 v[192:195], v[168:169], off offset:144
	v_mul_f32_e32 v170, v125, v125
	v_mul_f32_e32 v171, v127, v127
	v_mul_f32_e32 v172, v121, v121
	v_mul_f32_e32 v173, v123, v123
	v_mul_f32_e32 v174, v117, v117
	v_mul_f32_e32 v175, v119, v119
	v_mul_f32_e32 v176, v113, v113
	v_mul_f32_e32 v177, v115, v115
	v_fmac_f32_e32 v170, v124, v124
	v_fmac_f32_e32 v171, v126, v126
	v_fmac_f32_e32 v172, v120, v120
	v_fmac_f32_e32 v173, v122, v122
	v_fmac_f32_e32 v174, v116, v116
	v_fmac_f32_e32 v175, v118, v118
	v_fmac_f32_e32 v176, v112, v112
	v_fmac_f32_e32 v177, v114, v114
	v_add_f32_e32 v170, v170, v171
	v_add_f32_e32 v171, v172, v173
	v_add_f32_e32 v172, v174, v175
	v_add_f32_e32 v173, v176, v177
	v_add_f32_e32 v170, v170, v171
	v_add_f32_e32 v171, v172, v173
	v_add_f32_e32 v228, v170, v171
	v_cvt_pk_bf16_f32 v124, v124, v125
	v_cvt_pk_bf16_f32 v125, v126, v127
	v_cvt_pk_bf16_f32 v126, v120, v121
	v_cvt_pk_bf16_f32 v127, v122, v123
	v_cvt_pk_bf16_f32 v116, v116, v117
	v_cvt_pk_bf16_f32 v117, v118, v119
	v_cvt_pk_bf16_f32 v118, v112, v113
	v_cvt_pk_bf16_f32 v119, v114, v115
	s_not_b64 vcc, s[4:5]
	v_cndmask_b32_dpp v112, v124, v116, vcc row_ror:8 row_mask:0xf bank_mask:0xf
	v_cndmask_b32_dpp v113, v125, v117, vcc row_ror:8 row_mask:0xf bank_mask:0xf
	v_cndmask_b32_dpp v114, v126, v118, vcc row_ror:8 row_mask:0xf bank_mask:0xf
	v_cndmask_b32_dpp v115, v127, v119, vcc row_ror:8 row_mask:0xf bank_mask:0xf
	s_mov_b64 vcc, s[4:5]
	v_cndmask_b32_dpp v120, v116, v124, vcc row_ror:8 row_mask:0xf bank_mask:0xf
	v_cndmask_b32_dpp v121, v117, v125, vcc row_ror:8 row_mask:0xf bank_mask:0xf
	v_cndmask_b32_dpp v122, v118, v126, vcc row_ror:8 row_mask:0xf bank_mask:0xf
	v_cndmask_b32_dpp v123, v119, v127, vcc row_ror:8 row_mask:0xf bank_mask:0xf
	global_store_dwordx4 v[164:165], v[120:123], off nt
	s_mov_b32 s98, 0x4000
	v_lshl_add_u64 v[166:167], v[164:165], 0, s[98:99]
	global_store_dwordx4 v[166:167], v[112:115], off nt
	s_waitcnt vmcnt(14)
; __device__ __forceinline__ unsigned cvt_pk_bf16(float lo, float hi) { const cvt_f32x2_t v = {lo, hi}; const cvt_bf16x2_t b = __builtin_convertvector(v, cvt_bf16x2_t); return __builtin_bit_cast(unsigned, b); }
;     __device__ __forceinline__ void operator()(const f32x4 (&acc)[2][2][4][2], const Unit& u, int wr, int wc, int fr, int fq) const {
;     ...
;             for (int m = 0; m < 4; ++m) { const int rowg = u.pm * BM + ai * HALF + wr * 64 + m * 16, row = rowg + fr; const size_t off = (size_t)row * 1024 + col0;
;                 u32x4 w[2]; float ss = 0.f;
; #pragma unroll
;                 for (int bj = 0; bj < 2; ++bj) { f32x4 b0, b1;
;                     if (BASE_F32) { const float* bp = (const float*)base + off + 32 * bj; b0 = *(const f32x4*)bp; b1 = *(const f32x4*)(bp + 4); }
;                     else { const u32x4 bb = *(const u32x4*)((const bf16_t*)base + off + 32 * bj);
;                         b0 = (f32x4){__uint_as_float(bb.x << 16), __uint_as_float(bb.x & 0xffff0000u), __uint_as_float(bb.y << 16), __uint_as_float(bb.y & 0xffff0000u)};
;                         b1 = (f32x4){__uint_as_float(bb.z << 16), __uint_as_float(bb.z & 0xffff0000u), __uint_as_float(bb.w << 16), __uint_as_float(bb.w & 0xffff0000u)}; }
;                     const f32x4 o0 = b0 + acc[ai][bj][m][0], o1 = b1 + acc[ai][bj][m][1];
;                     ss += ((o0[0] * o0[0] + o0[1] * o0[1]) + (o0[2] * o0[2] + o0[3] * o0[3])) + ((o1[0] * o1[0] + o1[1] * o1[1]) + (o1[2] * o1[2] + o1[3] * o1[3]));
;                     w[bj].x = cvt_pk_bf16(o0[0], o0[1]); w[bj].y = cvt_pk_bf16(o0[2], o0[3]); w[bj].z = cvt_pk_bf16(o1[0], o1[1]); w[bj].w = cvt_pk_bf16(o1[2], o1[3]); }
;                 ss += __shfl_xor(ss, 16); ss += __shfl_xor(ss, 32); if (fq == 0) slots[(size_t)row * 16 + u.pn * 4 + wc] = ss;
;                 wide_store(xb, 1024, rowg, col0, fr, w[0], w[1]);
;                 if (m & 1) asm volatile("" ::: "memory"); }
	v_pk_add_f32 v[108:109], v[108:109], v[196:197]
	v_pk_add_f32 v[110:111], v[110:111], v[198:199]
	v_pk_add_f32 v[104:105], v[104:105], v[200:201]
	v_pk_add_f32 v[106:107], v[106:107], v[202:203]
	v_pk_add_f32 v[100:101], v[100:101], v[204:205]
	v_pk_add_f32 v[102:103], v[102:103], v[206:207]
	v_pk_add_f32 v[96:97], v[96:97], v[208:209]
	v_pk_add_f32 v[98:99], v[98:99], v[210:211]
	s_mov_b32 s98, 0x90000
	v_lshl_add_u64 v[168:169], v[234:235], 0, s[98:99]
	global_load_dwordx4 v[196:199], v[168:169], off
	global_load_dwordx4 v[200:203], v[168:169], off offset:16
	global_load_dwordx4 v[204:207], v[168:169], off offset:128
	global_load_dwordx4 v[208:211], v[168:169], off offset:144
	v_mul_f32_e32 v170, v109, v109
	v_mul_f32_e32 v171, v111, v111
	v_mul_f32_e32 v172, v105, v105
	v_mul_f32_e32 v173, v107, v107
	v_mul_f32_e32 v174, v101, v101
	v_mul_f32_e32 v175, v103, v103
	v_mul_f32_e32 v176, v97, v97
	v_mul_f32_e32 v177, v99, v99
	v_fmac_f32_e32 v170, v108, v108
	v_fmac_f32_e32 v171, v110, v110
	v_fmac_f32_e32 v172, v104, v104
	v_fmac_f32_e32 v173, v106, v106
	v_fmac_f32_e32 v174, v100, v100
	v_fmac_f32_e32 v175, v102, v102
	v_fmac_f32_e32 v176, v96, v96
	v_fmac_f32_e32 v177, v98, v98
	v_add_f32_e32 v170, v170, v171
	v_add_f32_e32 v171, v172, v173
	v_add_f32_e32 v172, v174, v175
	v_add_f32_e32 v173, v176, v177
	v_add_f32_e32 v170, v170, v171
	v_add_f32_e32 v171, v172, v173
	v_add_f32_e32 v229, v170, v171
	v_cvt_pk_bf16_f32 v108, v108, v109
	v_cvt_pk_bf16_f32 v109, v110, v111
	v_cvt_pk_bf16_f32 v110, v104, v105
	v_cvt_pk_bf16_f32 v111, v106, v107
	v_cvt_pk_bf16_f32 v100, v100, v101
	v_cvt_pk_bf16_f32 v101, v102, v103
	v_cvt_pk_bf16_f32 v102, v96, v97
	v_cvt_pk_bf16_f32 v103, v98, v99
	s_not_b64 vcc, s[4:5]
	v_cndmask_b32_dpp v96, v108, v100, vcc row_ror:8 row_mask:0xf bank_mask:0xf
	v_cndmask_b32_dpp v97, v109, v101, vcc row_ror:8 row_mask:0xf bank_mask:0xf
	v_cndmask_b32_dpp v98, v110, v102, vcc row_ror:8 row_mask:0xf bank_mask:0xf
	v_cndmask_b32_dpp v99, v111, v103, vcc row_ror:8 row_mask:0xf bank_mask:0xf
	s_mov_b64 vcc, s[4:5]
	v_cndmask_b32_dpp v104, v100, v108, vcc row_ror:8 row_mask:0xf bank_mask:0xf
	v_cndmask_b32_dpp v105, v101, v109, vcc row_ror:8 row_mask:0xf bank_mask:0xf
	v_cndmask_b32_dpp v106, v102, v110, vcc row_ror:8 row_mask:0xf bank_mask:0xf
	v_cndmask_b32_dpp v107, v103, v111, vcc row_ror:8 row_mask:0xf bank_mask:0xf
	s_mov_b32 s98, 0x4000
	v_lshl_add_u64 v[164:165], v[166:167], 0, s[98:99]
	global_store_dwordx4 v[164:165], v[104:107], off nt
	s_mov_b32 s98, 0x4000
	v_lshl_add_u64 v[166:167], v[164:165], 0, s[98:99]
	global_store_dwordx4 v[166:167], v[96:99], off nt
	s_waitcnt vmcnt(16)
	v_pk_add_f32 v[92:93], v[92:93], v[212:213]
	v_pk_add_f32 v[94:95], v[94:95], v[214:215]
	v_pk_add_f32 v[88:89], v[88:89], v[216:217]
	v_pk_add_f32 v[90:91], v[90:91], v[218:219]
	v_pk_add_f32 v[84:85], v[84:85], v[220:221]
	v_pk_add_f32 v[86:87], v[86:87], v[222:223]
	v_pk_add_f32 v[80:81], v[80:81], v[224:225]
	v_pk_add_f32 v[82:83], v[82:83], v[226:227]
	s_mov_b32 s98, 0xa0000
	v_lshl_add_u64 v[168:169], v[234:235], 0, s[98:99]
	global_load_dwordx4 v[212:215], v[168:169], off
	global_load_dwordx4 v[216:219], v[168:169], off offset:16
	global_load_dwordx4 v[220:223], v[168:169], off offset:128
	global_load_dwordx4 v[224:227], v[168:169], off offset:144
	v_mul_f32_e32 v170, v93, v93
	v_mul_f32_e32 v171, v95, v95
	v_mul_f32_e32 v172, v89, v89
	v_mul_f32_e32 v173, v91, v91
	v_mul_f32_e32 v174, v85, v85
	v_mul_f32_e32 v175, v87, v87
	v_mul_f32_e32 v176, v81, v81
	v_mul_f32_e32 v177, v83, v83
	v_fmac_f32_e32 v170, v92, v92
	v_fmac_f32_e32 v171, v94, v94
	v_fmac_f32_e32 v172, v88, v88
	v_fmac_f32_e32 v173, v90, v90
	v_fmac_f32_e32 v174, v84, v84
	v_fmac_f32_e32 v175, v86, v86
	v_fmac_f32_e32 v176, v80, v80
	v_fmac_f32_e32 v177, v82, v82
	v_add_f32_e32 v170, v170, v171
	v_add_f32_e32 v171, v172, v173
	v_add_f32_e32 v172, v174, v175
	v_add_f32_e32 v173, v176, v177
	v_add_f32_e32 v170, v170, v171
	v_add_f32_e32 v171, v172, v173
	v_add_f32_e32 v230, v170, v171
	v_cvt_pk_bf16_f32 v92, v92, v93
	v_cvt_pk_bf16_f32 v93, v94, v95
	v_cvt_pk_bf16_f32 v94, v88, v89
	v_cvt_pk_bf16_f32 v95, v90, v91
	v_cvt_pk_bf16_f32 v84, v84, v85
	v_cvt_pk_bf16_f32 v85, v86, v87
	v_cvt_pk_bf16_f32 v86, v80, v81
	v_cvt_pk_bf16_f32 v87, v82, v83
	s_not_b64 vcc, s[4:5]
	v_cndmask_b32_dpp v80, v92, v84, vcc row_ror:8 row_mask:0xf bank_mask:0xf
	v_cndmask_b32_dpp v81, v93, v85, vcc row_ror:8 row_mask:0xf bank_mask:0xf
	v_cndmask_b32_dpp v82, v94, v86, vcc row_ror:8 row_mask:0xf bank_mask:0xf
	v_cndmask_b32_dpp v83, v95, v87, vcc row_ror:8 row_mask:0xf bank_mask:0xf
	s_mov_b64 vcc, s[4:5]
	v_cndmask_b32_dpp v88, v84, v92, vcc row_ror:8 row_mask:0xf bank_mask:0xf
	v_cndmask_b32_dpp v89, v85, v93, vcc row_ror:8 row_mask:0xf bank_mask:0xf
	v_cndmask_b32_dpp v90, v86, v94, vcc row_ror:8 row_mask:0xf bank_mask:0xf
	v_cndmask_b32_dpp v91, v87, v95, vcc row_ror:8 row_mask:0xf bank_mask:0xf
	s_mov_b32 s98, 0x4000
	v_lshl_add_u64 v[164:165], v[166:167], 0, s[98:99]
	global_store_dwordx4 v[164:165], v[88:91], off nt
	s_mov_b32 s98, 0x4000
	v_lshl_add_u64 v[166:167], v[164:165], 0, s[98:99]
	global_store_dwordx4 v[166:167], v[80:83], off nt
	s_waitcnt vmcnt(18)
; __device__ __forceinline__ unsigned cvt_pk_bf16(float lo, float hi) { const cvt_f32x2_t v = {lo, hi}; const cvt_bf16x2_t b = __builtin_convertvector(v, cvt_bf16x2_t); return __builtin_bit_cast(unsigned, b); }
;     __device__ __forceinline__ void operator()(const f32x4 (&acc)[2][2][4][2], const Unit& u, int wr, int wc, int fr, int fq) const {
;     ...
;             for (int m = 0; m < 4; ++m) { const int rowg = u.pm * BM + ai * HALF + wr * 64 + m * 16, row = rowg + fr; const size_t off = (size_t)row * 1024 + col0;
;                 u32x4 w[2]; float ss = 0.f;
; #pragma unroll
;                 for (int bj = 0; bj < 2; ++bj) { f32x4 b0, b1;
;                     if (BASE_F32) { const float* bp = (const float*)base + off + 32 * bj; b0 = *(const f32x4*)bp; b1 = *(const f32x4*)(bp + 4); }
;                     else { const u32x4 bb = *(const u32x4*)((const bf16_t*)base + off + 32 * bj);
;                         b0 = (f32x4){__uint_as_float(bb.x << 16), __uint_as_float(bb.x & 0xffff0000u), __uint_as_float(bb.y << 16), __uint_as_float(bb.y & 0xffff0000u)};
;                         b1 = (f32x4){__uint_as_float(bb.z << 16), __uint_as_float(bb.z & 0xffff0000u), __uint_as_float(bb.w << 16), __uint_as_float(bb.w & 0xffff0000u)}; }
;                     const f32x4 o0 = b0 + acc[ai][bj][m][0], o1 = b1 + acc[ai][bj][m][1];
;                     ss += ((o0[0] * o0[0] + o0[1] * o0[1]) + (o0[2] * o0[2] + o0[3] * o0[3])) + ((o1[0] * o1[0] + o1[1] * o1[1]) + (o1[2] * o1[2] + o1[3] * o1[3]));
;                     w[bj].x = cvt_pk_bf16(o0[0], o0[1]); w[bj].y = cvt_pk_bf16(o0[2], o0[3]); w[bj].z = cvt_pk_bf16(o1[0], o1[1]); w[bj].w = cvt_pk_bf16(o1[2], o1[3]); }
;                 ss += __shfl_xor(ss, 16); ss += __shfl_xor(ss, 32); if (fq == 0) slots[(size_t)row * 16 + u.pn * 4 + wc] = ss;
;                 wide_store(xb, 1024, rowg, col0, fr, w[0], w[1]);
;                 if (m & 1) asm volatile("" ::: "memory"); }
	v_pk_add_f32 v[76:77], v[76:77], v[240:241]
	v_pk_add_f32 v[78:79], v[78:79], v[242:243]
	v_pk_add_f32 v[72:73], v[72:73], v[244:245]
	v_pk_add_f32 v[74:75], v[74:75], v[246:247]
	v_pk_add_f32 v[68:69], v[68:69], v[248:249]
	v_pk_add_f32 v[70:71], v[70:71], v[250:251]
	v_pk_add_f32 v[64:65], v[64:65], v[252:253]
	v_pk_add_f32 v[66:67], v[66:67], v[254:255]
	s_mov_b32 s98, 0xb0000
	v_lshl_add_u64 v[168:169], v[234:235], 0, s[98:99]
	global_load_dwordx4 v[240:243], v[168:169], off
	global_load_dwordx4 v[244:247], v[168:169], off offset:16
	global_load_dwordx4 v[248:251], v[168:169], off offset:128
	global_load_dwordx4 v[252:255], v[168:169], off offset:144
	v_mul_f32_e32 v170, v77, v77
	v_mul_f32_e32 v171, v79, v79
	v_mul_f32_e32 v172, v73, v73
	v_mul_f32_e32 v173, v75, v75
	v_mul_f32_e32 v174, v69, v69
	v_mul_f32_e32 v175, v71, v71
	v_mul_f32_e32 v176, v65, v65
	v_mul_f32_e32 v177, v67, v67
	v_fmac_f32_e32 v170, v76, v76
	v_fmac_f32_e32 v171, v78, v78
	v_fmac_f32_e32 v172, v72, v72
	v_fmac_f32_e32 v173, v74, v74
	v_fmac_f32_e32 v174, v68, v68
	v_fmac_f32_e32 v175, v70, v70
	v_fmac_f32_e32 v176, v64, v64
	v_fmac_f32_e32 v177, v66, v66
	v_add_f32_e32 v170, v170, v171
	v_add_f32_e32 v171, v172, v173
	v_add_f32_e32 v172, v174, v175
	v_add_f32_e32 v173, v176, v177
	v_add_f32_e32 v170, v170, v171
	v_add_f32_e32 v171, v172, v173
	v_add_f32_e32 v231, v170, v171
	v_cvt_pk_bf16_f32 v76, v76, v77
	v_cvt_pk_bf16_f32 v77, v78, v79
	v_cvt_pk_bf16_f32 v78, v72, v73
	v_cvt_pk_bf16_f32 v79, v74, v75
	v_cvt_pk_bf16_f32 v68, v68, v69
	v_cvt_pk_bf16_f32 v69, v70, v71
	v_cvt_pk_bf16_f32 v70, v64, v65
	v_cvt_pk_bf16_f32 v71, v66, v67
	s_not_b64 vcc, s[4:5]
	v_cndmask_b32_dpp v64, v76, v68, vcc row_ror:8 row_mask:0xf bank_mask:0xf
	v_cndmask_b32_dpp v65, v77, v69, vcc row_ror:8 row_mask:0xf bank_mask:0xf
	v_cndmask_b32_dpp v66, v78, v70, vcc row_ror:8 row_mask:0xf bank_mask:0xf
	v_cndmask_b32_dpp v67, v79, v71, vcc row_ror:8 row_mask:0xf bank_mask:0xf
	s_mov_b64 vcc, s[4:5]
	v_cndmask_b32_dpp v72, v68, v76, vcc row_ror:8 row_mask:0xf bank_mask:0xf
	v_cndmask_b32_dpp v73, v69, v77, vcc row_ror:8 row_mask:0xf bank_mask:0xf
	v_cndmask_b32_dpp v74, v70, v78, vcc row_ror:8 row_mask:0xf bank_mask:0xf
	v_cndmask_b32_dpp v75, v71, v79, vcc row_ror:8 row_mask:0xf bank_mask:0xf
	s_mov_b32 s98, 0x4000
	v_lshl_add_u64 v[164:165], v[166:167], 0, s[98:99]
	global_store_dwordx4 v[164:165], v[72:75], off nt
	s_mov_b32 s98, 0x4000
	v_lshl_add_u64 v[166:167], v[164:165], 0, s[98:99]
	global_store_dwordx4 v[166:167], v[64:67], off nt
	s_waitcnt vmcnt(20)
	v_pk_add_f32 v[60:61], v[60:61], v[180:181]
	v_pk_add_f32 v[62:63], v[62:63], v[182:183]
	v_pk_add_f32 v[56:57], v[56:57], v[184:185]
	v_pk_add_f32 v[58:59], v[58:59], v[186:187]
	v_pk_add_f32 v[52:53], v[52:53], v[188:189]
	v_pk_add_f32 v[54:55], v[54:55], v[190:191]
	v_pk_add_f32 v[48:49], v[48:49], v[192:193]
	v_pk_add_f32 v[50:51], v[50:51], v[194:195]
	v_mul_f32_e32 v170, v61, v61
	v_mul_f32_e32 v171, v63, v63
	v_mul_f32_e32 v172, v57, v57
	v_mul_f32_e32 v173, v59, v59
	v_mul_f32_e32 v174, v53, v53
	v_mul_f32_e32 v175, v55, v55
	v_mul_f32_e32 v176, v49, v49
	v_mul_f32_e32 v177, v51, v51
	v_fmac_f32_e32 v170, v60, v60
	v_fmac_f32_e32 v171, v62, v62
	v_fmac_f32_e32 v172, v56, v56
	v_fmac_f32_e32 v173, v58, v58
	v_fmac_f32_e32 v174, v52, v52
	v_fmac_f32_e32 v175, v54, v54
	v_fmac_f32_e32 v176, v48, v48
	v_fmac_f32_e32 v177, v50, v50
	v_add_f32_e32 v170, v170, v171
	v_add_f32_e32 v171, v172, v173
	v_add_f32_e32 v172, v174, v175
	v_add_f32_e32 v173, v176, v177
	v_add_f32_e32 v170, v170, v171
	v_add_f32_e32 v171, v172, v173
	v_add_f32_e32 v232, v170, v171
	v_cvt_pk_bf16_f32 v60, v60, v61
	v_cvt_pk_bf16_f32 v61, v62, v63
	v_cvt_pk_bf16_f32 v62, v56, v57
	v_cvt_pk_bf16_f32 v63, v58, v59
	v_cvt_pk_bf16_f32 v52, v52, v53
	v_cvt_pk_bf16_f32 v53, v54, v55
	v_cvt_pk_bf16_f32 v54, v48, v49
	v_cvt_pk_bf16_f32 v55, v50, v51
	s_not_b64 vcc, s[4:5]
	v_cndmask_b32_dpp v48, v60, v52, vcc row_ror:8 row_mask:0xf bank_mask:0xf
	v_cndmask_b32_dpp v49, v61, v53, vcc row_ror:8 row_mask:0xf bank_mask:0xf
	v_cndmask_b32_dpp v50, v62, v54, vcc row_ror:8 row_mask:0xf bank_mask:0xf
	v_cndmask_b32_dpp v51, v63, v55, vcc row_ror:8 row_mask:0xf bank_mask:0xf
	s_mov_b64 vcc, s[4:5]
	v_cndmask_b32_dpp v56, v52, v60, vcc row_ror:8 row_mask:0xf bank_mask:0xf
	v_cndmask_b32_dpp v57, v53, v61, vcc row_ror:8 row_mask:0xf bank_mask:0xf
	v_cndmask_b32_dpp v58, v54, v62, vcc row_ror:8 row_mask:0xf bank_mask:0xf
	v_cndmask_b32_dpp v59, v55, v63, vcc row_ror:8 row_mask:0xf bank_mask:0xf
	s_mov_b32 s98, 0x24000
	v_lshl_add_u64 v[164:165], v[166:167], 0, s[98:99]
	global_store_dwordx4 v[164:165], v[56:59], off nt
	s_mov_b32 s98, 0x4000
	v_lshl_add_u64 v[166:167], v[164:165], 0, s[98:99]
	global_store_dwordx4 v[166:167], v[48:51], off nt
	s_waitcnt vmcnt(16)
; __device__ __forceinline__ unsigned cvt_pk_bf16(float lo, float hi) { const cvt_f32x2_t v = {lo, hi}; const cvt_bf16x2_t b = __builtin_convertvector(v, cvt_bf16x2_t); return __builtin_bit_cast(unsigned, b); }
;     __device__ __forceinline__ void operator()(const f32x4 (&acc)[2][2][4][2], const Unit& u, int wr, int wc, int fr, int fq) const {
;     ...
;             for (int m = 0; m < 4; ++m) { const int rowg = u.pm * BM + ai * HALF + wr * 64 + m * 16, row = rowg + fr; const size_t off = (size_t)row * 1024 + col0;
;                 u32x4 w[2]; float ss = 0.f;
; #pragma unroll
;                 for (int bj = 0; bj < 2; ++bj) { f32x4 b0, b1;
;                     if (BASE_F32) { const float* bp = (const float*)base + off + 32 * bj; b0 = *(const f32x4*)bp; b1 = *(const f32x4*)(bp + 4); }
;                     else { const u32x4 bb = *(const u32x4*)((const bf16_t*)base + off + 32 * bj);
;                         b0 = (f32x4){__uint_as_float(bb.x << 16), __uint_as_float(bb.x & 0xffff0000u), __uint_as_float(bb.y << 16), __uint_as_float(bb.y & 0xffff0000u)};
;                         b1 = (f32x4){__uint_as_float(bb.z << 16), __uint_as_float(bb.z & 0xffff0000u), __uint_as_float(bb.w << 16), __uint_as_float(bb.w & 0xffff0000u)}; }
;                     const f32x4 o0 = b0 + acc[ai][bj][m][0], o1 = b1 + acc[ai][bj][m][1];
;                     ss += ((o0[0] * o0[0] + o0[1] * o0[1]) + (o0[2] * o0[2] + o0[3] * o0[3])) + ((o1[0] * o1[0] + o1[1] * o1[1]) + (o1[2] * o1[2] + o1[3] * o1[3]));
;                     w[bj].x = cvt_pk_bf16(o0[0], o0[1]); w[bj].y = cvt_pk_bf16(o0[2], o0[3]); w[bj].z = cvt_pk_bf16(o1[0], o1[1]); w[bj].w = cvt_pk_bf16(o1[2], o1[3]); }
;                 ss += __shfl_xor(ss, 16); ss += __shfl_xor(ss, 32); if (fq == 0) slots[(size_t)row * 16 + u.pn * 4 + wc] = ss;
;                 wide_store(xb, 1024, rowg, col0, fr, w[0], w[1]);
;                 if (m & 1) asm volatile("" ::: "memory"); }
	v_pk_add_f32 v[44:45], v[44:45], v[196:197]
	v_pk_add_f32 v[46:47], v[46:47], v[198:199]
	v_pk_add_f32 v[40:41], v[40:41], v[200:201]
	v_pk_add_f32 v[42:43], v[42:43], v[202:203]
	v_pk_add_f32 v[36:37], v[36:37], v[204:205]
	v_pk_add_f32 v[38:39], v[38:39], v[206:207]
	v_pk_add_f32 v[32:33], v[32:33], v[208:209]
	v_pk_add_f32 v[34:35], v[34:35], v[210:211]
	v_mul_f32_e32 v170, v45, v45
	v_mul_f32_e32 v171, v47, v47
	v_mul_f32_e32 v172, v41, v41
	v_mul_f32_e32 v173, v43, v43
	v_mul_f32_e32 v174, v37, v37
	v_mul_f32_e32 v175, v39, v39
	v_mul_f32_e32 v176, v33, v33
	v_mul_f32_e32 v177, v35, v35
	v_fmac_f32_e32 v170, v44, v44
	v_fmac_f32_e32 v171, v46, v46
	v_fmac_f32_e32 v172, v40, v40
	v_fmac_f32_e32 v173, v42, v42
	v_fmac_f32_e32 v174, v36, v36
	v_fmac_f32_e32 v175, v38, v38
	v_fmac_f32_e32 v176, v32, v32
	v_fmac_f32_e32 v177, v34, v34
	v_add_f32_e32 v170, v170, v171
	v_add_f32_e32 v171, v172, v173
	v_add_f32_e32 v172, v174, v175
	v_add_f32_e32 v173, v176, v177
	v_add_f32_e32 v170, v170, v171
	v_add_f32_e32 v171, v172, v173
	v_add_f32_e32 v233, v170, v171
	v_cvt_pk_bf16_f32 v44, v44, v45
	v_cvt_pk_bf16_f32 v45, v46, v47
	v_cvt_pk_bf16_f32 v46, v40, v41
	v_cvt_pk_bf16_f32 v47, v42, v43
	v_cvt_pk_bf16_f32 v36, v36, v37
	v_cvt_pk_bf16_f32 v37, v38, v39
	v_cvt_pk_bf16_f32 v38, v32, v33
	v_cvt_pk_bf16_f32 v39, v34, v35
	s_not_b64 vcc, s[4:5]
	v_cndmask_b32_dpp v32, v44, v36, vcc row_ror:8 row_mask:0xf bank_mask:0xf
	v_cndmask_b32_dpp v33, v45, v37, vcc row_ror:8 row_mask:0xf bank_mask:0xf
	v_cndmask_b32_dpp v34, v46, v38, vcc row_ror:8 row_mask:0xf bank_mask:0xf
	v_cndmask_b32_dpp v35, v47, v39, vcc row_ror:8 row_mask:0xf bank_mask:0xf
	s_mov_b64 vcc, s[4:5]
	v_cndmask_b32_dpp v40, v36, v44, vcc row_ror:8 row_mask:0xf bank_mask:0xf
	v_cndmask_b32_dpp v41, v37, v45, vcc row_ror:8 row_mask:0xf bank_mask:0xf
	v_cndmask_b32_dpp v42, v38, v46, vcc row_ror:8 row_mask:0xf bank_mask:0xf
	v_cndmask_b32_dpp v43, v39, v47, vcc row_ror:8 row_mask:0xf bank_mask:0xf
	s_mov_b32 s98, 0x4000
	v_lshl_add_u64 v[164:165], v[166:167], 0, s[98:99]
	global_store_dwordx4 v[164:165], v[40:43], off nt
	s_mov_b32 s98, 0x4000
	v_lshl_add_u64 v[166:167], v[164:165], 0, s[98:99]
	global_store_dwordx4 v[166:167], v[32:35], off nt
	s_waitcnt vmcnt(12)
	v_pk_add_f32 v[28:29], v[28:29], v[212:213]
	v_pk_add_f32 v[30:31], v[30:31], v[214:215]
	v_pk_add_f32 v[24:25], v[24:25], v[216:217]
	v_pk_add_f32 v[26:27], v[26:27], v[218:219]
	v_pk_add_f32 v[20:21], v[20:21], v[220:221]
	v_pk_add_f32 v[22:23], v[22:23], v[222:223]
	v_pk_add_f32 v[16:17], v[16:17], v[224:225]
	v_pk_add_f32 v[18:19], v[18:19], v[226:227]
	v_mul_f32_e32 v170, v29, v29
	v_mul_f32_e32 v171, v31, v31
	v_mul_f32_e32 v172, v25, v25
	v_mul_f32_e32 v173, v27, v27
	v_mul_f32_e32 v174, v21, v21
	v_mul_f32_e32 v175, v23, v23
	v_mul_f32_e32 v176, v17, v17
	v_mul_f32_e32 v177, v19, v19
	v_fmac_f32_e32 v170, v28, v28
	v_fmac_f32_e32 v171, v30, v30
	v_fmac_f32_e32 v172, v24, v24
	v_fmac_f32_e32 v173, v26, v26
	v_fmac_f32_e32 v174, v20, v20
	v_fmac_f32_e32 v175, v22, v22
	v_fmac_f32_e32 v176, v16, v16
	v_fmac_f32_e32 v177, v18, v18
	v_add_f32_e32 v170, v170, v171
	v_add_f32_e32 v171, v172, v173
	v_add_f32_e32 v172, v174, v175
	v_add_f32_e32 v173, v176, v177
	v_add_f32_e32 v170, v170, v171
	v_add_f32_e32 v171, v172, v173
	v_add_f32_e32 v179, v170, v171
	v_cvt_pk_bf16_f32 v28, v28, v29
	v_cvt_pk_bf16_f32 v29, v30, v31
	v_cvt_pk_bf16_f32 v30, v24, v25
	v_cvt_pk_bf16_f32 v31, v26, v27
	v_cvt_pk_bf16_f32 v20, v20, v21
	v_cvt_pk_bf16_f32 v21, v22, v23
	v_cvt_pk_bf16_f32 v22, v16, v17
	v_cvt_pk_bf16_f32 v23, v18, v19
	s_not_b64 vcc, s[4:5]
	v_cndmask_b32_dpp v16, v28, v20, vcc row_ror:8 row_mask:0xf bank_mask:0xf
	v_cndmask_b32_dpp v17, v29, v21, vcc row_ror:8 row_mask:0xf bank_mask:0xf
	v_cndmask_b32_dpp v18, v30, v22, vcc row_ror:8 row_mask:0xf bank_mask:0xf
	v_cndmask_b32_dpp v19, v31, v23, vcc row_ror:8 row_mask:0xf bank_mask:0xf
	s_mov_b64 vcc, s[4:5]
	v_cndmask_b32_dpp v24, v20, v28, vcc row_ror:8 row_mask:0xf bank_mask:0xf
	v_cndmask_b32_dpp v25, v21, v29, vcc row_ror:8 row_mask:0xf bank_mask:0xf
	v_cndmask_b32_dpp v26, v22, v30, vcc row_ror:8 row_mask:0xf bank_mask:0xf
	v_cndmask_b32_dpp v27, v23, v31, vcc row_ror:8 row_mask:0xf bank_mask:0xf
	s_mov_b32 s98, 0x4000
	v_lshl_add_u64 v[164:165], v[166:167], 0, s[98:99]
	global_store_dwordx4 v[164:165], v[24:27], off nt
	s_mov_b32 s98, 0x4000
	v_lshl_add_u64 v[166:167], v[164:165], 0, s[98:99]
	global_store_dwordx4 v[166:167], v[16:19], off nt
	s_waitcnt vmcnt(8)
; __device__ __forceinline__ unsigned cvt_pk_bf16(float lo, float hi) { const cvt_f32x2_t v = {lo, hi}; const cvt_bf16x2_t b = __builtin_convertvector(v, cvt_bf16x2_t); return __builtin_bit_cast(unsigned, b); }
;     __device__ __forceinline__ void operator()(const f32x4 (&acc)[2][2][4][2], const Unit& u, int wr, int wc, int fr, int fq) const {
;     ...
;             for (int m = 0; m < 4; ++m) { const int rowg = u.pm * BM + ai * HALF + wr * 64 + m * 16, row = rowg + fr; const size_t off = (size_t)row * 1024 + col0;
;                 u32x4 w[2]; float ss = 0.f;
; #pragma unroll
;                 for (int bj = 0; bj < 2; ++bj) { f32x4 b0, b1;
;                     if (BASE_F32) { const float* bp = (const float*)base + off + 32 * bj; b0 = *(const f32x4*)bp; b1 = *(const f32x4*)(bp + 4); }
;                     else { const u32x4 bb = *(const u32x4*)((const bf16_t*)base + off + 32 * bj);
;                         b0 = (f32x4){__uint_as_float(bb.x << 16), __uint_as_float(bb.x & 0xffff0000u), __uint_as_float(bb.y << 16), __uint_as_float(bb.y & 0xffff0000u)};
;                         b1 = (f32x4){__uint_as_float(bb.z << 16), __uint_as_float(bb.z & 0xffff0000u), __uint_as_float(bb.w << 16), __uint_as_float(bb.w & 0xffff0000u)}; }
;                     const f32x4 o0 = b0 + acc[ai][bj][m][0], o1 = b1 + acc[ai][bj][m][1];
;                     ss += ((o0[0] * o0[0] + o0[1] * o0[1]) + (o0[2] * o0[2] + o0[3] * o0[3])) + ((o1[0] * o1[0] + o1[1] * o1[1]) + (o1[2] * o1[2] + o1[3] * o1[3]));
;                     w[bj].x = cvt_pk_bf16(o0[0], o0[1]); w[bj].y = cvt_pk_bf16(o0[2], o0[3]); w[bj].z = cvt_pk_bf16(o1[0], o1[1]); w[bj].w = cvt_pk_bf16(o1[2], o1[3]); }
;                 ss += __shfl_xor(ss, 16); ss += __shfl_xor(ss, 32); if (fq == 0) slots[(size_t)row * 16 + u.pn * 4 + wc] = ss;
;                 wide_store(xb, 1024, rowg, col0, fr, w[0], w[1]);
;                 if (m & 1) asm volatile("" ::: "memory"); }
	v_pk_add_f32 v[12:13], v[12:13], v[240:241]
	v_pk_add_f32 v[14:15], v[14:15], v[242:243]
	v_pk_add_f32 v[8:9], v[8:9], v[244:245]
	v_pk_add_f32 v[10:11], v[10:11], v[246:247]
	v_pk_add_f32 v[4:5], v[4:5], v[248:249]
	v_pk_add_f32 v[6:7], v[6:7], v[250:251]
	v_pk_add_f32 v[0:1], v[0:1], v[252:253]
	v_pk_add_f32 v[2:3], v[2:3], v[254:255]
	v_mul_f32_e32 v170, v13, v13
	v_mul_f32_e32 v171, v15, v15
	v_mul_f32_e32 v172, v9, v9
	v_mul_f32_e32 v173, v11, v11
	v_mul_f32_e32 v174, v5, v5
	v_mul_f32_e32 v175, v7, v7
	v_mul_f32_e32 v176, v1, v1
	v_mul_f32_e32 v177, v3, v3
	v_fmac_f32_e32 v170, v12, v12
	v_fmac_f32_e32 v171, v14, v14
	v_fmac_f32_e32 v172, v8, v8
	v_fmac_f32_e32 v173, v10, v10
	v_fmac_f32_e32 v174, v4, v4
	v_fmac_f32_e32 v175, v6, v6
	v_fmac_f32_e32 v176, v0, v0
	v_fmac_f32_e32 v177, v2, v2
	v_add_f32_e32 v170, v170, v171
	v_add_f32_e32 v171, v172, v173
	v_add_f32_e32 v172, v174, v175
	v_add_f32_e32 v173, v176, v177
	v_add_f32_e32 v170, v170, v171
	v_add_f32_e32 v171, v172, v173
	v_add_f32_e32 v238, v170, v171
	v_cvt_pk_bf16_f32 v12, v12, v13
	v_cvt_pk_bf16_f32 v13, v14, v15
	v_cvt_pk_bf16_f32 v14, v8, v9
	v_cvt_pk_bf16_f32 v15, v10, v11
	v_cvt_pk_bf16_f32 v4, v4, v5
	v_cvt_pk_bf16_f32 v5, v6, v7
	v_cvt_pk_bf16_f32 v6, v0, v1
	v_cvt_pk_bf16_f32 v7, v2, v3
	s_not_b64 vcc, s[4:5]
	v_cndmask_b32_dpp v0, v12, v4, vcc row_ror:8 row_mask:0xf bank_mask:0xf
	v_cndmask_b32_dpp v1, v13, v5, vcc row_ror:8 row_mask:0xf bank_mask:0xf
	v_cndmask_b32_dpp v2, v14, v6, vcc row_ror:8 row_mask:0xf bank_mask:0xf
	v_cndmask_b32_dpp v3, v15, v7, vcc row_ror:8 row_mask:0xf bank_mask:0xf
	s_mov_b64 vcc, s[4:5]
	v_cndmask_b32_dpp v8, v4, v12, vcc row_ror:8 row_mask:0xf bank_mask:0xf
	v_cndmask_b32_dpp v9, v5, v13, vcc row_ror:8 row_mask:0xf bank_mask:0xf
	v_cndmask_b32_dpp v10, v6, v14, vcc row_ror:8 row_mask:0xf bank_mask:0xf
	v_cndmask_b32_dpp v11, v7, v15, vcc row_ror:8 row_mask:0xf bank_mask:0xf
	s_mov_b32 s98, 0x4000
	v_lshl_add_u64 v[164:165], v[166:167], 0, s[98:99]
	global_store_dwordx4 v[164:165], v[8:11], off nt
	s_mov_b32 s98, 0x4000
	v_lshl_add_u64 v[166:167], v[164:165], 0, s[98:99]
	global_store_dwordx4 v[166:167], v[0:3], off nt
	ds_bpermute_b32 v170, v161, v228
	ds_bpermute_b32 v171, v161, v229
	ds_bpermute_b32 v172, v161, v230
	ds_bpermute_b32 v173, v161, v231
	ds_bpermute_b32 v174, v161, v232
	ds_bpermute_b32 v175, v161, v233
	ds_bpermute_b32 v176, v161, v179
	ds_bpermute_b32 v177, v161, v238
	s_waitcnt lgkmcnt(0)
	v_add_f32_e32 v228, v228, v170
	v_add_f32_e32 v229, v229, v171
	v_add_f32_e32 v230, v230, v172
	v_add_f32_e32 v231, v231, v173
	v_add_f32_e32 v232, v232, v174
	v_add_f32_e32 v233, v233, v175
	v_add_f32_e32 v179, v179, v176
	v_add_f32_e32 v238, v238, v177
	ds_bpermute_b32 v170, v178, v228
	ds_bpermute_b32 v171, v178, v229
	ds_bpermute_b32 v172, v178, v230
	ds_bpermute_b32 v173, v178, v231
	ds_bpermute_b32 v174, v178, v232
	ds_bpermute_b32 v175, v178, v233
	ds_bpermute_b32 v176, v178, v179
	ds_bpermute_b32 v177, v178, v238
	s_waitcnt lgkmcnt(0)
	v_add_f32_e32 v228, v228, v170
	v_add_f32_e32 v229, v229, v171
	v_add_f32_e32 v230, v230, v172
	v_add_f32_e32 v231, v231, v173
	v_add_f32_e32 v232, v232, v174
	v_add_f32_e32 v233, v233, v175
	v_add_f32_e32 v179, v179, v176
	v_add_f32_e32 v238, v238, v177
	s_and_saveexec_b64 s[20:21], s[2:3]
	global_store_dword v[236:237], v228, off
	global_store_dword v[236:237], v229, off offset:1024
	global_store_dword v[236:237], v230, off offset:2048
	global_store_dword v[236:237], v231, off offset:3072
	s_mov_b32 s98, 0x2000
	v_lshl_add_u64 v[236:237], v[236:237], 0, s[98:99]
	global_store_dword v[236:237], v232, off
	global_store_dword v[236:237], v233, off offset:1024
	global_store_dword v[236:237], v179, off offset:2048
	global_store_dword v[236:237], v238, off offset:3072
	s_or_b64 exec, exec, s[20:21]
	s_mov_b64 s[0:1], -1
	s_andn2_b64 vcc, exec, s[6:7]
	s_cbranch_vccnz .LBB0_577
	s_andn2_b64 vcc, exec, s[12:13]
	s_cbranch_vccnz .LBB0_576
	s_barrier
	s_branch .LBB0_576
